# p3a S2 (beta, cumulative log-decay) computed once per unit by all eight waves (one v head each) instead of by two waves in every k-head iteration
# baseline (speedup 1.0000x reference)
.LBB0_500:
	v_lshlrev_b32_e32 v20, 16, v114
	v_and_b32_e32 v21, 0xffff0000, v114
	v_lshlrev_b32_e32 v34, 16, v118
	v_and_b32_e32 v35, 0xffff0000, v118
	s_waitcnt vmcnt(6)
	v_pk_fma_f32 v[20:21], v[6:7], v[20:21], 0 op_sel_hi:[1,1,0]
	v_lshlrev_b32_e32 v42, 16, v122
	v_and_b32_e32 v43, 0xffff0000, v122
	s_waitcnt vmcnt(5)
	v_pk_fma_f32 v[20:21], v[10:11], v[34:35], v[20:21]
	v_lshlrev_b32_e32 v50, 16, v126
	v_and_b32_e32 v51, 0xffff0000, v126
	s_waitcnt vmcnt(3)
	v_pk_fma_f32 v[20:21], v[98:99], v[42:43], v[20:21]
	v_lshlrev_b32_e32 v32, 16, v119
	s_waitcnt vmcnt(1)
	v_pk_fma_f32 v[20:21], v[106:107], v[50:51], v[20:21]
	v_and_b32_e32 v33, 0xffff0000, v119
	v_mul_f32_e32 v22, 0xbfb8aa3b, v20
	v_mul_f32_e32 v23, 0xbfb8aa3b, v21
	v_exp_f32_e32 v22, v22
	v_exp_f32_e32 v23, v23
	v_lshlrev_b32_e32 v40, 16, v123
	v_and_b32_e32 v41, 0xffff0000, v123
	v_add_f32_e32 v22, 1.0, v22
	v_add_f32_e32 v23, 1.0, v23
	v_rcp_f32_e32 v22, v22
	v_rcp_f32_e32 v23, v23
	v_lshlrev_b32_e32 v46, 16, v127
	v_and_b32_e32 v47, 0xffff0000, v127
	v_lshlrev_b32_e32 v52, 16, v116
	v_pk_mul_f32 v[20:21], v[20:21], v[22:23]
	v_lshlrev_b32_e32 v22, 16, v115
	v_and_b32_e32 v23, 0xffff0000, v115
	v_pk_fma_f32 v[22:23], v[8:9], v[22:23], 0 op_sel_hi:[1,1,0]
	v_and_b32_e32 v53, 0xffff0000, v116
	v_pk_fma_f32 v[22:23], v[12:13], v[32:33], v[22:23]
	v_lshlrev_b32_e32 v30, 16, v120
	v_pk_fma_f32 v[22:23], v[100:101], v[40:41], v[22:23]
	v_and_b32_e32 v31, 0xffff0000, v120
	v_pk_fma_f32 v[22:23], v[108:109], v[46:47], v[22:23]
	v_pk_fma_f32 v[52:53], v[2:3], v[52:53], 0 op_sel_hi:[1,1,0]
	v_mul_f32_e32 v24, 0xbfb8aa3b, v22
	v_exp_f32_e32 v26, v24
	v_mul_f32_e32 v24, 0xbfb8aa3b, v23
	v_exp_f32_e32 v27, v24
	v_lshlrev_b32_e32 v38, 16, v124
	v_and_b32_e32 v39, 0xffff0000, v124
	v_pk_fma_f32 v[52:53], v[14:15], v[30:31], v[52:53]
	v_lshlrev_b32_e32 v48, 16, v128
	v_and_b32_e32 v49, 0xffff0000, v128
	v_pk_fma_f32 v[52:53], v[102:103], v[38:39], v[52:53]
	v_add_f32_e32 v26, 1.0, v26
	s_waitcnt vmcnt(0)
	s_cmp_eq_u32 s64, 0
	s_cbranch_scc0 .Lp3a_s2h_skip
	s_or_b32 s98, s64, s84
	s_lshl_b32 s98, s98, 1
	v_readlane_b32 s99, v249, 49
	v_readlane_b32 s100, v249, 47
	v_readlane_b32 s101, v249, 48
	v_mov_b32_e32 v244, v1
	v_mov_b32_e32 v245, 0
	s_or_b32 s98, s98, s99
	s_lshl_b32 s98, s98, 2
	v_lshl_add_u64 v[244:245], s[88:89], 0, v[244:245]
	s_add_u32 s100, s100, s98
	s_addc_u32 s101, s101, 0
	v_lshlrev_b64 v[244:245], 8, v[244:245]
	s_nop 1
	v_lshl_add_u64 v[244:245], s[100:101], 0, v[244:245]
	s_add_u32 s100, s60, s98
	s_addc_u32 s101, s61, 0
	global_load_dword v240, v[244:245], off
	global_load_dword v241, v[244:245], off offset:128
	global_load_dword v242, v18, s[100:101]
	s_add_u32 s100, s58, s98
	s_addc_u32 s101, s59, 0
	global_load_dword v243, v18, s[100:101]

.LBB0_534:
	s_or_b64 exec, exec, s[8:9]
	s_cmp_eq_u32 s64, 0
	s_cbranch_scc0 .Lp3a_s2w_skip
	s_waitcnt vmcnt(0)

.LBB0_587:
	s_or_b32 s42, s64, s84
	s_cmp_eq_u32 s64, 0
	s_cbranch_scc1 .LBB0_612
	s_branch .LBB0_615

.LBB0_611:
	s_waitcnt vmcnt(6)
	v_mov_b64_e32 v[72:73], v[8:9]
	v_mov_b64_e32 v[68:69], v[4:5]
	s_waitcnt vmcnt(5)
	v_mov_b64_e32 v[76:77], v[12:13]
	s_waitcnt vmcnt(4)
	v_mov_b64_e32 v[80:81], v[16:17]
	s_waitcnt vmcnt(3)
	v_mov_b64_e32 v[82:83], v[98:99]
	s_waitcnt vmcnt(2)
	v_mov_b64_e32 v[86:87], v[102:103]
	s_waitcnt vmcnt(1)
	v_mov_b64_e32 v[90:91], v[106:107]
	s_waitcnt vmcnt(0)
	v_mov_b64_e32 v[94:95], v[110:111]
	v_mov_b64_e32 v[22:23], v[114:115]
	v_mov_b64_e32 v[26:27], v[118:119]
	v_mov_b64_e32 v[30:31], v[122:123]
	v_mov_b64_e32 v[34:35], v[126:127]
	v_mov_b64_e32 v[38:39], v[130:131]
	v_mov_b64_e32 v[42:43], v[134:135]
	v_mov_b64_e32 v[46:47], v[138:139]
	v_mov_b64_e32 v[50:51], v[142:143]
	v_mov_b64_e32 v[54:55], v[146:147]
	v_mov_b64_e32 v[58:59], v[150:151]
	v_mov_b64_e32 v[62:63], v[154:155]
	v_mov_b64_e32 v[70:71], v[6:7]
	v_mov_b64_e32 v[66:67], v[2:3]
	v_mov_b64_e32 v[74:75], v[10:11]
	v_mov_b64_e32 v[78:79], v[14:15]
	v_mov_b64_e32 v[84:85], v[100:101]
	v_mov_b64_e32 v[88:89], v[104:105]
	v_mov_b64_e32 v[92:93], v[108:109]
	v_mov_b64_e32 v[96:97], v[112:113]
	v_mov_b64_e32 v[24:25], v[116:117]
	v_mov_b64_e32 v[28:29], v[120:121]
	v_mov_b64_e32 v[32:33], v[124:125]
	v_mov_b64_e32 v[36:37], v[128:129]
	v_mov_b64_e32 v[40:41], v[132:133]
	v_mov_b64_e32 v[44:45], v[136:137]
	v_mov_b64_e32 v[48:49], v[140:141]
	v_mov_b64_e32 v[52:53], v[144:145]
	v_mov_b64_e32 v[56:57], v[148:149]
	v_mov_b64_e32 v[60:61], v[152:153]
	v_mov_b64_e32 v[64:65], v[156:157]
	s_or_b32 s42, s64, s84
	s_branch .LBB0_615

.LBB0_614:
	s_or_b64 exec, exec, s[10:11]
	s_add_u32 s8, s58, s8
	s_addc_u32 s9, s59, s9
	v_mov_b32_e32 v4, v243
	v_add_u32_e32 v6, -1, v184
	v_cmp_lt_i32_e32 vcc, v6, v167
	v_mul_f32_e32 v2, 0xbfb8aa3b, v2
	v_exp_f32_e32 v2, v2
	v_cndmask_b32_e32 v6, v6, v184, vcc
	v_lshlrev_b32_e32 v6, 2, v6
	v_cmp_gt_i32_e32 vcc, 1, v160
	v_add_f32_e32 v2, 1.0, v2
	v_rcp_f32_e32 v2, v2
	v_mul_f32_e32 v4, 0x3fb8aa3b, v4
	v_exp_f32_e32 v4, v4
	s_nop 0
	v_mul_f32_e64 v5, v3, -v4
	ds_bpermute_b32 v6, v6, v5
	s_waitcnt lgkmcnt(0)
	v_fma_f32 v3, v3, -v4, v6
	v_add_u32_e32 v4, -2, v184
	v_cndmask_b32_e32 v3, v3, v5, vcc
	v_cmp_lt_i32_e32 vcc, v4, v167
	s_nop 1
	v_cndmask_b32_e32 v4, v4, v184, vcc
	v_lshlrev_b32_e32 v4, 2, v4
	ds_bpermute_b32 v4, v4, v3
	v_cmp_gt_i32_e32 vcc, 2, v160
	s_waitcnt lgkmcnt(0)
	v_add_f32_e32 v4, v3, v4
	v_cndmask_b32_e32 v3, v4, v3, vcc
	v_add_u32_e32 v4, -4, v184
	v_cmp_lt_i32_e32 vcc, v4, v167
	s_nop 1
	v_cndmask_b32_e32 v4, v4, v184, vcc
	v_lshlrev_b32_e32 v4, 2, v4
	ds_bpermute_b32 v4, v4, v3
	v_cmp_gt_i32_e32 vcc, 4, v160
	s_waitcnt lgkmcnt(0)
	v_add_f32_e32 v4, v3, v4
	v_cndmask_b32_e32 v3, v4, v3, vcc
	v_add_u32_e32 v4, -8, v184
	v_cmp_lt_i32_e32 vcc, v4, v167
	s_nop 1
	v_cndmask_b32_e32 v4, v4, v184, vcc
	v_lshlrev_b32_e32 v4, 2, v4
	ds_bpermute_b32 v4, v4, v3
	v_cmp_gt_i32_e32 vcc, 8, v160
	s_waitcnt lgkmcnt(0)
	v_add_f32_e32 v4, v3, v4
	v_cndmask_b32_e32 v3, v4, v3, vcc
	v_add_u32_e32 v4, -16, v184
	v_cmp_lt_i32_e32 vcc, v4, v167
	s_nop 1
	v_cndmask_b32_e32 v4, v4, v184, vcc
	v_lshlrev_b32_e32 v4, 2, v4
	ds_bpermute_b32 v4, v4, v3
	s_waitcnt lgkmcnt(0)
	v_add_f32_e32 v4, v3, v4
	v_cndmask_b32_e64 v3, v4, v3, s[6:7]
	v_subrev_u32_e32 v4, 32, v184
	v_cmp_lt_i32_e32 vcc, v4, v167
	s_nop 1
	v_cndmask_b32_e32 v4, v4, v184, vcc
	v_lshlrev_b32_e32 v4, 2, v4
	ds_bpermute_b32 v4, v4, v3
	s_waitcnt lgkmcnt(0)
	v_add_f32_e32 v4, v3, v4
	v_cndmask_b32_e64 v4, v4, v3, s[4:5]
	s_lshl_b32 s4, s64, 7
	v_readlane_b32 s5, v249, 4
	s_or_b32 s4, s4, s5
	v_add_u32_e32 v3, s4, v160
	s_add_i32 s4, s40, s72
	s_lshr_b32 s5, s4, 4
	s_cmp_eq_u32 s5, 2
	s_cselect_b32 s6, s17, 0x26000000
	s_cmp_lg_u32 s5, 1
	s_cselect_b32 s5, s6, 0x1d000000
	s_cmp_gt_u32 s4, 15
	ds_bpermute_b32 v5, v192, v4
	s_cselect_b32 s4, s5, 0x1ed00000
	s_add_u32 s4, s70, s4
	v_lshl_add_u32 v3, v3, 2, 0
	s_addc_u32 s5, s71, 0
	s_lshl_b32 s6, s40, 6
	v_add_u32_e32 v6, 0x20800, v3
	s_and_b32 s6, s6, 0x3c0
	ds_write_b32 v6, v2
	v_add_u32_e32 v2, 0x21000, v3
	s_add_i32 s6, s6, s85
	ds_write_b32 v2, v4
	s_mul_hi_i32 s7, s6, 0x7400
	s_mulk_i32 s6, 0x7400
	v_mul_f32_e32 v2, 0x3fb8aa3b, v4
	s_waitcnt lgkmcnt(2)
	v_sub_f32_e32 v4, v5, v4
	s_add_u32 s4, s4, s6
	v_mul_f32_e32 v4, 0x3fb8aa3b, v4
	s_addc_u32 s5, s5, s7
	v_exp_f32_e32 v6, v2
	v_exp_f32_e32 v4, v4
	v_lshl_add_u64 v[2:3], v[160:161], 2, s[4:5]
	v_add_co_u32_e32 v2, vcc, 0x7000, v2
	s_nop 1
	v_addc_co_u32_e32 v3, vcc, 0, v3, vcc
	global_store_dword v[2:3], v6, off sc1
	global_store_dword v[2:3], v4, off offset:256 sc1
